# NA next-unit warm-up trimmed to the two cold neighbourhood dummy loads (probe: -3.8us in NA vs 4 loads)
# speedup vs baseline: 1.0029x; 1.0029x over previous
.LBB0_1387:
	s_or_b64 exec, exec, s[4:5]
	v_lshrrev_b32_e32 v14, 2, v2
	v_ashrrev_i32_e32 v17, 8, v2
	v_and_b32_e32 v20, 48, v14
	v_add_u32_e32 v19, s6, v17
	v_sub_u32_e64 v14, v20, 8 clamp
	v_min_u32_e32 v140, 32, v14
	v_lshlrev_b32_e32 v14, 6, v19
	s_and_b32 s36, s34, 30
	v_and_b32_e32 v139, 15, v2
	v_ashrrev_i32_e32 v15, 31, v14
	v_sub_u32_e64 v0, s36, 4 clamp
	v_lshl_add_u64 v[14:15], s[0:1], 0, v[14:15]
	v_or_b32_e32 v20, v20, v139
	v_min_u32_e32 v0, 24, v0
	v_or_b32_e32 v14, v20, v14
	s_lshl_b32 s4, s7, 6
	v_lshlrev_b32_e32 v13, 13, v0
	v_max_i32_e32 v0, 4, v19
	v_lshlrev_b64 v[118:119], 9, v[14:15]
	v_lshlrev_b64 v[14:15], 10, v[14:15]
	v_add_u32_e32 v0, -4, v0
	v_bfe_u32 v98, v2, 4, 2
	v_lshl_add_u64 v[14:15], s[64:65], 0, v[14:15]
	s_lshl_b32 s26, s4, 1
	v_min_u32_e32 v21, 24, v0
	v_lshl_add_u64 v[14:15], v[14:15], 0, s[26:27]
	v_lshlrev_b32_e32 v0, 4, v98
	v_lshl_add_u64 v[14:15], v[14:15], 0, v[0:1]
	v_sub_u32_e64 v14, v20, 8 clamp
	v_lshlrev_b32_e32 v141, 2, v98
	v_min_u32_e32 v14, 48, v14
	v_add_u32_e32 v15, v140, v141
	v_add_u32_e32 v66, 16, v14
	v_sub_u32_e32 v67, v15, v20
	v_cmp_ge_u32_e32 vcc, v15, v14
	v_cmp_lt_u32_e64 s[0:1], v15, v66
	v_med3_i32 v142, v67, -15, 15
	v_or_b32_e32 v67, 1, v15
	s_and_b64 s[4:5], vcc, s[0:1]
	v_cmp_ge_u32_e32 vcc, v67, v14
	v_cmp_lt_u32_e64 s[0:1], v67, v66
	v_sub_u32_e32 v67, v67, v20
	v_med3_i32 v143, v67, -15, 15
	v_or_b32_e32 v67, 2, v15
	s_and_b64 s[6:7], vcc, s[0:1]
	v_cmp_ge_u32_e32 vcc, v67, v14
	v_cmp_lt_u32_e64 s[0:1], v67, v66
	v_sub_u32_e32 v67, v67, v20
	v_med3_i32 v144, v67, -15, 15
	v_or_b32_e32 v67, 3, v15
	s_and_b64 s[8:9], vcc, s[0:1]
	v_cmp_ge_u32_e32 vcc, v67, v14
	v_cmp_lt_u32_e64 s[0:1], v67, v66
	v_sub_u32_e32 v67, v67, v20
	v_med3_i32 v145, v67, -15, 15
	v_add_u32_e32 v67, 16, v15
	s_and_b64 s[10:11], vcc, s[0:1]
	v_cmp_ge_u32_e32 vcc, v67, v14
	v_sub_u32_e32 v67, v67, v20
	v_cmp_lt_u32_e64 s[0:1], v15, v14
	v_med3_i32 v146, v67, -15, 15
	v_add_u32_e32 v67, 17, v15
	s_and_b64 s[12:13], vcc, s[0:1]
	v_cmp_ge_u32_e32 vcc, v67, v14
	v_cmp_lt_u32_e64 s[0:1], v67, v66
	v_sub_u32_e32 v67, v67, v20
	v_med3_i32 v147, v67, -15, 15
	v_add_u32_e32 v67, 18, v15
	s_and_b64 s[14:15], vcc, s[0:1]
	v_cmp_ge_u32_e32 vcc, v67, v14
	v_cmp_lt_u32_e64 s[0:1], v67, v66
	v_add_u32_e32 v15, 19, v15
	s_and_b64 s[16:17], vcc, s[0:1]
	v_cmp_ge_u32_e32 vcc, v15, v14
	v_cmp_lt_u32_e64 s[0:1], v15, v66
	v_or_b32_e32 v120, 0x1d400, v0
	v_sub_u32_e32 v67, v67, v20
	s_and_b64 s[18:19], vcc, s[0:1]
	v_mad_u32_u24 v0, v139, s42, v120
	v_cmp_lt_i32_e32 vcc, v135, v136
	v_med3_i32 v148, v67, -15, 15
	s_waitcnt lgkmcnt(0)
	s_barrier
	s_add_i32 s98, s48, 1
	s_lshl_b32 s98, s98, 3
	s_or_b32 s98, s98, s3
	s_mul_i32 s98, s98, s21
	s_add_i32 s98, s98, s20
	s_min_i32 s98, s98, 0x7ff
	s_bfe_u32 s99, s98, 0x30004
	s_lshl_b32 s99, s99, 7
	s_and_b32 s100, s98, 15
	s_lshl_b32 s100, s100, 1
	s_sub_i32 s100, s100, 4
	s_max_i32 s100, s100, 0
	s_min_i32 s100, s100, 24
	s_lshl_b32 s100, s100, 6
	s_ashr_i32 s101, s98, 7
	s_lshl_b32 s98, s101, 11
	s_add_i32 s100, s100, s98
	s_lshl_b32 s101, s101, 8
	s_add_i32 s101, s101, 0x8000
	v_cmp_gt_u32_e32 vcc, 0x100, v162
	v_mov_b32_e32 v238, 0x4400000
	v_mov_b32_e32 v239, 0x2000000
	s_nop 0
	v_cndmask_b32_e32 v238, v239, v238, vcc
	v_add_u32_e32 v238, s99, v238
	v_and_b32_e32 v236, 0xff, v162
	v_and_b32_e32 v237, 63, v162
	v_add_u32_e32 v240, s101, v236
	v_lshl_add_u32 v240, v240, 10, v238
	v_mov_b32_e32 v241, 0
	v_add_u32_e32 v242, s100, v236
	v_lshl_add_u32 v242, v242, 10, v238
	v_mov_b32_e32 v243, 0
	v_add_u32_e32 v244, 0x40000, v242
	v_mov_b32_e32 v245, 0
	v_add_u32_e32 v237, s100, v237
	v_add_u32_e32 v237, 0x200, v237
	v_lshl_add_u32 v236, v237, 10, v238
	v_mov_b32_e32 v237, 0
	v_lshl_add_u64 v[240:241], s[64:65], 0, v[240:241]
	v_lshl_add_u64 v[242:243], s[64:65], 0, v[242:243]
	v_lshl_add_u64 v[244:245], s[64:65], 0, v[244:245]
	v_lshl_add_u64 v[236:237], s[64:65], 0, v[236:237]
	global_load_dword v216, v[242:243], off
	global_load_dword v217, v[244:245], off
	ds_read_b128 v[66:69], v0
	ds_read_b128 v[70:73], v0 offset:64
	ds_read_b128 v[74:77], v0 offset:2304
	ds_read_b128 v[78:81], v0 offset:2368
	ds_read_b128 v[82:85], v0 offset:4608
	ds_read_b128 v[86:89], v0 offset:4672
	ds_read_b128 v[90:93], v0 offset:6912
	ds_read_b128 v[94:97], v0 offset:6976
	v_cndmask_b32_e32 v0, v134, v135, vcc
	v_cmp_lt_i32_e32 vcc, v137, v136
	v_lshlrev_b32_e32 v150, 2, v0
	v_sub_u32_e32 v153, v21, v7
	v_cndmask_b32_e32 v0, v134, v137, vcc
	v_lshlrev_b32_e32 v151, 2, v0
	v_bfe_u32 v0, v2, 2, 2
	v_or_b32_e32 v0, v141, v0
	v_mul_u32_u24_e32 v152, 0x90, v0
	v_lshlrev_b32_e32 v0, 2, v2
	v_sub_u32_e32 v14, v15, v20
	v_and_b32_e32 v20, 12, v0
	v_lshl_or_b32 v0, v153, 6, v140
	v_add_lshl_u32 v0, v0, v139, 7
	v_add_u32_e32 v154, 0x14400, v0
	v_add_u32_e32 v157, 0x14c00, v0
	v_add_u32_e32 v158, 0x16400, v0
	v_add_u32_e32 v159, 0x16c00, v0
	v_xor_b32_e32 v0, v3, v2
	v_lshlrev_b32_e32 v0, 4, v0
	v_and_b32_e32 v0, 0x70, v0
	v_lshl_or_b32 v0, v3, 7, v0
	v_add_u32_e32 v161, 0x14400, v0
	v_xor_b32_e32 v0, v4, v2
	v_lshlrev_b32_e32 v0, 4, v0
	v_and_b32_e32 v0, 0x70, v0
	v_lshl_or_b32 v0, v4, 7, v0
	v_add_u32_e32 v164, 0x14400, v0
	v_xor_b32_e32 v0, v5, v2
	v_lshlrev_b32_e32 v0, 4, v0
	v_and_b32_e32 v0, 0x70, v0
	v_lshl_or_b32 v0, v5, 7, v0
	v_add_u32_e32 v165, 0x14400, v0
	v_xor_b32_e32 v0, v6, v2
	v_lshlrev_b32_e32 v0, 4, v0
	v_and_b32_e32 v0, 0x70, v0
	v_lshl_or_b32 v0, v6, 7, v0
	v_add_u32_e32 v166, 0x14400, v0
	v_xor_b32_e32 v0, v12, v2
	v_lshlrev_b32_e32 v0, 4, v0
	v_and_b32_e32 v0, 0x70, v0
	v_lshl_or_b32 v0, v12, 7, v0
	v_add_u32_e32 v167, 0x14400, v0
	v_xor_b32_e32 v0, v11, v2
	v_lshlrev_b32_e32 v0, 4, v0
	v_and_b32_e32 v0, 0x70, v0
	v_lshl_or_b32 v0, v11, 7, v0
	v_add_u32_e32 v168, 0x14400, v0
	v_xor_b32_e32 v0, v10, v2
	v_lshlrev_b32_e32 v0, 4, v0
	v_and_b32_e32 v0, 0x70, v0
	v_lshl_or_b32 v0, v10, 7, v0
	v_add_u32_e32 v169, 0x14400, v0
	v_xor_b32_e32 v0, v9, v2
	v_lshlrev_b32_e32 v0, 4, v0
	v_and_b32_e32 v0, 0x70, v0
	v_lshl_or_b32 v0, v9, 7, v0
	v_add_u32_e32 v170, 0x14400, v0
	v_xor_b32_e32 v0, v8, v2
	v_lshlrev_b32_e32 v0, 4, v0
	v_and_b32_e32 v0, 0x70, v0
	v_lshl_or_b32 v0, v8, 7, v0
	v_add_u32_e32 v171, 0x14400, v0
	v_add_u32_e32 v0, s36, v17
	v_max_i32_e32 v0, 4, v0
	v_lshrrev_b32_e32 v16, 4, v2
	v_and_b32_e32 v7, 7, v2
	v_add_u32_e32 v0, -4, v0
	v_med3_i32 v149, v14, -15, 15
	v_bitop3_b32 v14, v16, v7, 3 bitop3:0x6c
	v_bitop3_b32 v7, v98, v7, 4 bitop3:0x36
	v_min_u32_e32 v0, 24, v0
	v_add_lshl_u32 v2, v140, v139, 7
	v_lshlrev_b32_e32 v155, 4, v14
	v_lshlrev_b32_e32 v156, 4, v7
	v_lshl_add_u32 v0, v0, 13, v2
	v_or_b32_e32 v2, v0, v156
	v_or_b32_e32 v0, v0, v155
	v_sub_u32_e32 v173, v2, v13
	v_sub_u32_e32 v174, v0, v13
	v_mov_b32_e32 v2, v1
	v_mov_b32_e32 v3, v1
	v_mov_b32_e32 v4, v1
	v_mov_b32_e32 v5, v1
	v_mov_b32_e32 v6, v1
	v_mov_b32_e32 v7, v1
	v_mov_b32_e32 v8, v1
	v_mov_b32_e32 v9, v1
	v_mov_b32_e32 v10, v1
	v_mov_b32_e32 v11, v1
	v_mov_b32_e32 v12, v1
	v_mov_b32_e32 v13, v1
	v_mov_b32_e32 v14, v1
	v_mov_b32_e32 v15, v1
	v_mov_b32_e32 v0, v1
	v_mov_b64_e32 v[16:17], v[14:15]
	s_mov_b32 s28, 0
	v_sub_u32_e32 v160, v21, v19
	v_or_b32_e32 v172, 64, v140
	v_mov_b32_e32 v98, v1
	v_mov_b32_e32 v99, v1
	v_mov_b32_e32 v100, v1
	v_mov_b32_e32 v101, v1
	v_mov_b32_e32 v175, 0
	s_mov_b32 s49, 0x15600
	v_lshlrev_b32_e32 v176, 1, v20
	s_mov_b32 s50, 0
	v_mov_b64_e32 v[14:15], v[12:13]
	v_mov_b64_e32 v[12:13], v[10:11]
	v_mov_b64_e32 v[10:11], v[8:9]
	v_mov_b64_e32 v[8:9], v[6:7]
	v_mov_b64_e32 v[6:7], v[4:5]
	v_mov_b64_e32 v[4:5], v[2:3]
	v_mov_b64_e32 v[2:3], v[0:1]
	s_branch .LBB0_1389

.LBB0_1391:
	v_xor_b32_e32 v106, 0x80000000, v175
	v_mov_b32_e32 v107, v106
	v_mov_b32_e32 v108, v106
	v_mov_b32_e32 v109, v106
	s_and_b32 s51, s50, 3
	s_cmp_eq_u32 s51, 3
	s_waitcnt vmcnt(3) lgkmcnt(7)
	v_mfma_f32_16x16x32_bf16 v[102:105], v[66:69], v[58:61], v[106:109]
	s_waitcnt vmcnt(2) lgkmcnt(6)
	v_mfma_f32_16x16x32_bf16 v[110:113], v[70:73], v[62:65], v[102:105]
	s_waitcnt lgkmcnt(5)
	v_mfma_f32_16x16x32_bf16 v[102:105], v[74:77], v[58:61], v[106:109]
	s_waitcnt lgkmcnt(4)
	v_mfma_f32_16x16x32_bf16 v[114:117], v[78:81], v[62:65], v[102:105]
	s_waitcnt lgkmcnt(3)
	v_mfma_f32_16x16x32_bf16 v[102:105], v[82:85], v[58:61], v[106:109]
	s_waitcnt lgkmcnt(1)
	v_mfma_f32_16x16x32_bf16 v[106:109], v[90:93], v[58:61], v[106:109]
	v_mfma_f32_16x16x32_bf16 v[102:105], v[86:89], v[62:65], v[102:105]
	s_waitcnt lgkmcnt(0)
	v_mfma_f32_16x16x32_bf16 v[106:109], v[94:97], v[62:65], v[106:109]
	s_cbranch_scc1 .LBB0_1397
	s_cmp_gt_u32 s50, 2
	s_mov_b64 s[0:1], -1
	s_cbranch_scc0 .LBB0_1394
	v_add_u32_e32 v21, s28, v174
	v_add_u32_e32 v70, s28, v173
	v_add_u32_e32 v20, 0x8400, v21
	v_add_u32_e32 v0, 0x8400, v70
	v_add_u32_e32 v19, 0x8c00, v21
	v_add_u32_e32 v66, 0x8c00, v70
	v_add_u32_e32 v67, 0xa400, v21
	v_add_u32_e32 v68, 0xa400, v70
	v_add_u32_e32 v69, 0xac00, v21
	v_add_u32_e32 v21, 0xac00, v70
	s_mov_b64 s[0:1], 0
